# lane-local rescale test: cross-half max exchange + new-max candidate moved to the rare rescale path; first row-sum add folded
# speedup vs baseline: 1.0027x; 1.0027x over previous
.LBB0_309:
	s_mov_b32 s77, s74
	s_add_u32 s4, s70, 0xffffc000
	s_mov_b32 s74, s72
	s_addc_u32 s5, s71, -1
	s_add_i32 s72, s72, s42
	s_setprio 1
	s_waitcnt lgkmcnt(4)
	v_mfma_f32_32x32x16_bf16 v[112:127], v[234:237], v[188:191], 0
	ds_read_b128 v[234:237], v233 offset:57344
	v_add_f32_e32 v1, v232, v230
	v_add_f32_e32 v1, v228, v1
	v_add_f32_e32 v1, v231, v1
	v_add_f32_e32 v1, v226, v1
	s_waitcnt lgkmcnt(4)
	v_mfma_f32_32x32x16_bf16 v[96:111], v[238:241], v[188:191], 0
	ds_read_b128 v[238:241], v254 offset:49152
	v_add_f32_e32 v1, v229, v1
	v_add_f32_e32 v1, v225, v1
	v_add_f32_e32 v1, v227, v1
	v_add_f32_e32 v1, v222, v1
	v_add_f32_e32 v1, v224, v1
	s_waitcnt lgkmcnt(4)
	v_mfma_f32_32x32x16_bf16 v[112:127], v[242:245], v[184:187], v[112:127]
	ds_read_b128 v[242:245], v254 offset:57344
	s_mov_b32 s73, m0
	s_mov_b32 m0, s72
	s_nop 0
	global_load_lds_dwordx4 v197, s[4:5]
	s_mov_b32 m0, s73
	v_add_f32_e32 v1, v220, v1
	v_add_f32_e32 v1, v223, v1
	v_exp_f32_e32 v2, v128
	v_add_f32_e32 v1, v218, v1
	s_waitcnt lgkmcnt(4)
	v_mfma_f32_32x32x16_bf16 v[96:111], v[246:249], v[184:187], v[96:111]
	ds_read_b128 v[246:249], v215 offset:49280
	v_exp_f32_e32 v12, v129
	v_add_f32_e32 v1, v221, v1
	v_exp_f32_e32 v13, v130
	v_add_f32_e32 v1, v217, v1
	s_waitcnt lgkmcnt(4)
	v_mfma_f32_32x32x16_bf16 v[112:127], v[250:253], v[180:183], v[112:127]
	ds_read_b128 v[250:253], v215 offset:57472
	v_exp_f32_e32 v14, v131
	v_add_f32_e32 v1, v219, v1
	v_exp_f32_e32 v15, v132
	s_waitcnt lgkmcnt(4)
	v_mfma_f32_32x32x16_bf16 v[96:111], v[234:237], v[180:183], v[96:111]
	ds_read_b128 v[234:237], v216 offset:49280
	s_addk_i32 s72, 0x400
	s_mov_b32 s73, m0
	s_mov_b32 m0, s72
	s_nop 0
	global_load_lds_dwordx4 v198, s[4:5]
	s_mov_b32 m0, s73
	v_add_f32_e32 v1, v2, v1
	v_exp_f32_e32 v18, v133
	v_add_f32_e32 v1, v12, v1
	s_waitcnt lgkmcnt(4)
	v_mfma_f32_32x32x16_bf16 v[112:127], v[238:241], v[176:179], v[112:127]
	ds_read_b128 v[238:241], v216 offset:57472
	v_exp_f32_e32 v19, v134
	v_add_f32_e32 v1, v13, v1
	v_exp_f32_e32 v20, v135
	v_add_f32_e32 v1, v14, v1
	s_waitcnt lgkmcnt(4)
	v_mfma_f32_32x32x16_bf16 v[96:111], v[242:245], v[176:179], v[96:111]
	ds_read_b128 v[242:245], v233 offset:49280
	v_exp_f32_e32 v21, v136
	v_add_f32_e32 v1, v15, v1
	v_exp_f32_e32 v22, v137
	s_waitcnt lgkmcnt(4)
	v_mfma_f32_32x32x16_bf16 v[112:127], v[246:249], v[172:175], v[112:127]
	ds_read_b128 v[246:249], v233 offset:57472
	s_add_i32 s4, s69, s97
	s_mov_b32 s5, m0
	s_mov_b32 m0, s4
	s_nop 0
	global_load_lds_dwordx4 v199, s[56:57]
	s_mov_b32 m0, s5
	v_add_f32_e32 v1, v18, v1
	v_exp_f32_e32 v23, v138
	v_add_f32_e32 v1, v19, v1
	v_exp_f32_e32 v24, v139
	s_waitcnt lgkmcnt(4)
	v_mfma_f32_32x32x16_bf16 v[96:111], v[250:253], v[172:175], v[96:111]
	ds_read_b128 v[250:253], v254 offset:49280
	v_add_f32_e32 v1, v20, v1
	v_exp_f32_e32 v25, v140
	v_add_f32_e32 v1, v21, v1
	s_waitcnt lgkmcnt(4)
	v_mfma_f32_32x32x16_bf16 v[112:127], v[234:237], v[168:171], v[112:127]
	ds_read_b128 v[234:237], v254 offset:57472
	v_exp_f32_e32 v26, v141
	v_add_f32_e32 v1, v22, v1
	v_exp_f32_e32 v27, v142
	v_add_f32_e32 v1, v23, v1
	s_waitcnt lgkmcnt(4)
	v_mfma_f32_32x32x16_bf16 v[96:111], v[238:241], v[168:171], v[96:111]
	s_addk_i32 s4, 0x400
	s_mov_b32 s5, m0
	s_mov_b32 m0, s4
	s_nop 0
	global_load_lds_dwordx4 v200, s[56:57]
	s_mov_b32 m0, s5
	v_exp_f32_e32 v28, v143
	v_add_f32_e32 v1, v24, v1
	v_add_f32_e32 v1, v25, v1
	v_add_f32_e32 v1, v26, v1
	s_waitcnt lgkmcnt(3)
	v_mfma_f32_32x32x16_bf16 v[112:127], v[242:245], v[164:167], v[112:127]
	v_add_f32_e32 v1, v27, v1
	v_add_f32_e32 v1, v28, v1
	v_mov_b32_e32 v3, v1
	v_cvt_pk_bf16_f32 v4, v230, v232
	v_cvt_pk_bf16_f32 v5, v228, v231
	s_waitcnt lgkmcnt(2)
	v_mfma_f32_32x32x16_bf16 v[96:111], v[246:249], v[164:167], v[96:111]
	v_cvt_pk_bf16_f32 v6, v226, v229
	s_nop 1
	v_permlane32_swap_b32_e32 v1, v3
	v_cvt_pk_bf16_f32 v7, v225, v227
	v_cvt_pk_bf16_f32 v8, v222, v224
	v_cvt_pk_bf16_f32 v9, v220, v223
	s_waitcnt lgkmcnt(1)
	v_mfma_f32_32x32x16_bf16 v[112:127], v[250:253], v[160:163], v[112:127]
	v_cvt_pk_bf16_f32 v10, v218, v221
	v_cvt_pk_bf16_f32 v11, v217, v219
	v_cvt_pk_bf16_f32 v12, v2, v12
	v_cvt_pk_bf16_f32 v13, v13, v14
	v_cvt_pk_bf16_f32 v14, v15, v18
	s_waitcnt lgkmcnt(0)
	v_mfma_f32_32x32x16_bf16 v[96:111], v[234:237], v[160:163], v[96:111]
	v_cvt_pk_bf16_f32 v15, v19, v20
	v_cvt_pk_bf16_f32 v18, v21, v22
	v_cvt_pk_bf16_f32 v19, v23, v24
	v_cvt_pk_bf16_f32 v20, v25, v26
	v_cvt_pk_bf16_f32 v21, v27, v28
	s_setprio 0
	v_add_u32_e32 v2, s74, v206
	ds_read_b64_tr_b16 v[22:23], v2 offset:0
	ds_read_b64_tr_b16 v[24:25], v2 offset:0x800
	ds_read_b64_tr_b16 v[26:27], v2 offset:0x1000
	ds_read_b64_tr_b16 v[28:29], v2 offset:0x1800
	ds_read_b64_tr_b16 v[128:129], v2 offset:0x2000
	ds_read_b64_tr_b16 v[130:131], v2 offset:0x2800
	ds_read_b64_tr_b16 v[132:133], v2 offset:0x3000
	ds_read_b64_tr_b16 v[134:135], v2 offset:0x3800
	s_waitcnt lgkmcnt(6)
	s_nop 0
	v_mfma_f32_32x32x16_bf16 v[32:47], v[4:7], v[22:25], v[32:47]
	ds_read_b64_tr_b16 v[22:23], v2 offset:0x200
	ds_read_b64_tr_b16 v[24:25], v2 offset:0xa00
	s_waitcnt lgkmcnt(6)
	v_mfma_f32_32x32x16_bf16 v[32:47], v[8:11], v[26:29], v[32:47]
	ds_read_b64_tr_b16 v[26:27], v2 offset:0x1200
	ds_read_b64_tr_b16 v[28:29], v2 offset:0x1a00
	s_waitcnt lgkmcnt(6)
	v_mfma_f32_32x32x16_bf16 v[32:47], v[12:15], v[128:131], v[32:47]
	ds_read_b64_tr_b16 v[128:129], v2 offset:0x2200
	ds_read_b64_tr_b16 v[130:131], v2 offset:0x2a00
	s_waitcnt lgkmcnt(6)
	v_mfma_f32_32x32x16_bf16 v[32:47], v[18:21], v[132:135], v[32:47]
	ds_read_b64_tr_b16 v[132:133], v2 offset:0x3200
	ds_read_b64_tr_b16 v[134:135], v2 offset:0x3a00
	s_waitcnt lgkmcnt(6)
	v_mfma_f32_32x32x16_bf16 v[48:63], v[4:7], v[22:25], v[48:63]
	ds_read_b64_tr_b16 v[22:23], v2 offset:0x400
	ds_read_b64_tr_b16 v[24:25], v2 offset:0xc00
	s_waitcnt lgkmcnt(6)
	v_mfma_f32_32x32x16_bf16 v[48:63], v[8:11], v[26:29], v[48:63]
	ds_read_b64_tr_b16 v[26:27], v2 offset:0x1400
	ds_read_b64_tr_b16 v[28:29], v2 offset:0x1c00
	s_waitcnt lgkmcnt(6)
	v_mfma_f32_32x32x16_bf16 v[48:63], v[12:15], v[128:131], v[48:63]
	ds_read_b64_tr_b16 v[128:129], v2 offset:0x2400
	ds_read_b64_tr_b16 v[130:131], v2 offset:0x2c00
	s_waitcnt lgkmcnt(6)
	v_mfma_f32_32x32x16_bf16 v[48:63], v[18:21], v[132:135], v[48:63]
	ds_read_b64_tr_b16 v[132:133], v2 offset:0x3400
	ds_read_b64_tr_b16 v[134:135], v2 offset:0x3c00
	s_waitcnt lgkmcnt(6)
	v_mfma_f32_32x32x16_bf16 v[64:79], v[4:7], v[22:25], v[64:79]
	ds_read_b64_tr_b16 v[22:23], v2 offset:0x600
	ds_read_b64_tr_b16 v[24:25], v2 offset:0xe00
	v_add3_u32 v215, s69, v209, v208
	s_waitcnt lgkmcnt(6)
	v_mfma_f32_32x32x16_bf16 v[64:79], v[8:11], v[26:29], v[64:79]
	ds_read_b64_tr_b16 v[26:27], v2 offset:0x1600
	ds_read_b64_tr_b16 v[28:29], v2 offset:0x1e00
	v_add3_u32 v216, s69, v210, v208
	s_waitcnt lgkmcnt(6)
	v_mfma_f32_32x32x16_bf16 v[64:79], v[12:15], v[128:131], v[64:79]
	ds_read_b64_tr_b16 v[128:129], v2 offset:0x2600
	ds_read_b64_tr_b16 v[130:131], v2 offset:0x2e00
	v_add3_u32 v233, s69, v211, v208
	s_waitcnt lgkmcnt(6)
	v_mfma_f32_32x32x16_bf16 v[64:79], v[18:21], v[132:135], v[64:79]
	ds_read_b64_tr_b16 v[132:133], v2 offset:0x3600
	ds_read_b64_tr_b16 v[134:135], v2 offset:0x3e00
	v_add3_u32 v254, s69, v212, v208
	s_waitcnt lgkmcnt(6)
	v_mfma_f32_32x32x16_bf16 v[80:95], v[4:7], v[22:25], v[80:95]
	v_max_f32_e32 v2, v113, v112
	v_max3_f32 v2, v2, v114, v115
	v_max3_f32 v2, v2, v116, v117
	v_max3_f32 v2, v2, v118, v119
	v_max3_f32 v2, v2, v120, v121
	v_max3_f32 v2, v2, v122, v123
	v_max3_f32 v2, v2, v124, v125
	v_max3_f32 v2, v2, v126, v127
	s_waitcnt lgkmcnt(4)
	v_mfma_f32_32x32x16_bf16 v[80:95], v[8:11], v[26:29], v[80:95]
	v_max3_f32 v2, v2, v96, v97
	v_max3_f32 v2, v2, v98, v99
	v_max3_f32 v2, v2, v100, v101
	v_max3_f32 v2, v2, v102, v103
	v_max3_f32 v2, v2, v104, v105
	v_max3_f32 v2, v2, v106, v107
	v_max3_f32 v2, v2, v108, v109
	v_max3_f32 v2, v2, v110, v111
	s_waitcnt lgkmcnt(2)
	v_mfma_f32_32x32x16_bf16 v[80:95], v[12:15], v[128:131], v[80:95]
	v_sub_f32_e32 v4, v2, v214
	v_cmp_ge_f32_e32 vcc, 0x42b504f3, v4
	s_waitcnt lgkmcnt(0)
	v_mfma_f32_32x32x16_bf16 v[80:95], v[18:21], v[132:135], v[80:95]
	s_cmp_eq_u64 vcc, exec
	s_cbranch_scc0 .Lattn0_slowA
	v_mov_b32_e32 v4, 1.0
	v_mov_b32_e32 v2, v214
.Lattn0_backA:
	s_waitcnt vmcnt(4) lgkmcnt(0)
	s_barrier
	ds_read_b128 v[234:237], v215 offset:49152
	ds_read_b128 v[238:241], v215 offset:57344
	ds_read_b128 v[242:245], v216 offset:49152
	ds_read_b128 v[246:249], v216 offset:57344
	ds_read_b128 v[250:253], v233 offset:49152
	v_mul_f32_e32 v5, 0xbe0293ee, v2
	v_fmamk_f32 v6, v112, 0x3e0293ee, v5
	v_fmamk_f32 v7, v113, 0x3e0293ee, v5
	v_fmamk_f32 v8, v114, 0x3e0293ee, v5
	v_fmamk_f32 v9, v115, 0x3e0293ee, v5
	v_fmamk_f32 v10, v116, 0x3e0293ee, v5
	v_fmamk_f32 v11, v117, 0x3e0293ee, v5
	v_fmamk_f32 v12, v118, 0x3e0293ee, v5
	v_fmamk_f32 v13, v119, 0x3e0293ee, v5
	v_fmamk_f32 v14, v120, 0x3e0293ee, v5
	v_fmamk_f32 v15, v121, 0x3e0293ee, v5
	v_fmamk_f32 v18, v122, 0x3e0293ee, v5
	v_fmamk_f32 v19, v123, 0x3e0293ee, v5
	v_fmamk_f32 v20, v124, 0x3e0293ee, v5
	v_fmamk_f32 v21, v125, 0x3e0293ee, v5
	v_fmamk_f32 v22, v126, 0x3e0293ee, v5
	v_fmamk_f32 v23, v127, 0x3e0293ee, v5
	v_fmamk_f32 v24, v96, 0x3e0293ee, v5
	v_fmamk_f32 v25, v97, 0x3e0293ee, v5
	v_fmamk_f32 v26, v98, 0x3e0293ee, v5
	v_fmamk_f32 v27, v99, 0x3e0293ee, v5
	v_fmamk_f32 v28, v100, 0x3e0293ee, v5
	v_fmamk_f32 v29, v101, 0x3e0293ee, v5
	v_fmamk_f32 v30, v102, 0x3e0293ee, v5
	v_fmamk_f32 v31, v103, 0x3e0293ee, v5
	v_fmamk_f32 v128, v104, 0x3e0293ee, v5
	v_fmamk_f32 v129, v105, 0x3e0293ee, v5
	v_fmamk_f32 v130, v106, 0x3e0293ee, v5
	v_fmamk_f32 v131, v107, 0x3e0293ee, v5
	v_fmamk_f32 v132, v108, 0x3e0293ee, v5
	v_fmamk_f32 v133, v109, 0x3e0293ee, v5
	v_fmamk_f32 v134, v110, 0x3e0293ee, v5
	v_fmac_f32_e32 v5, 0x3e0293ee, v111
	s_setprio 1
	s_waitcnt lgkmcnt(4)
	v_mfma_f32_32x32x16_bf16 v[112:127], v[234:237], v[188:191], 0
	ds_read_b128 v[234:237], v233 offset:57344
	v_exp_f32_e32 v135, v6
	v_exp_f32_e32 v136, v7
	v_exp_f32_e32 v137, v8
	v_exp_f32_e32 v138, v9
	s_waitcnt lgkmcnt(4)
	v_mfma_f32_32x32x16_bf16 v[96:111], v[238:241], v[188:191], 0
	ds_read_b128 v[238:241], v254 offset:49152
	v_exp_f32_e32 v10, v10
	v_exp_f32_e32 v11, v11
	v_exp_f32_e32 v12, v12
	s_waitcnt lgkmcnt(4)
	v_mfma_f32_32x32x16_bf16 v[112:127], v[242:245], v[184:187], v[112:127]
	ds_read_b128 v[242:245], v254 offset:57344
	s_add_i32 s4, s77, s42
	s_mov_b32 s5, m0
	s_mov_b32 m0, s4
	s_nop 0
	global_load_lds_dwordx4 v197, s[70:71]
	s_mov_b32 m0, s5
	v_exp_f32_e32 v13, v13
	v_exp_f32_e32 v14, v14
	v_exp_f32_e32 v15, v15
	v_exp_f32_e32 v18, v18
	s_waitcnt lgkmcnt(4)
	v_mfma_f32_32x32x16_bf16 v[96:111], v[246:249], v[184:187], v[96:111]
	ds_read_b128 v[246:249], v215 offset:49280
	v_exp_f32_e32 v19, v19
	v_exp_f32_e32 v20, v20
	v_exp_f32_e32 v21, v21
	s_waitcnt lgkmcnt(4)
	v_mfma_f32_32x32x16_bf16 v[112:127], v[250:253], v[180:183], v[112:127]
	ds_read_b128 v[250:253], v215 offset:57472
	v_exp_f32_e32 v22, v22
	v_exp_f32_e32 v23, v23
	v_exp_f32_e32 v7, v24
	v_exp_f32_e32 v24, v25
	s_waitcnt lgkmcnt(4)
	v_mfma_f32_32x32x16_bf16 v[96:111], v[234:237], v[180:183], v[96:111]
	ds_read_b128 v[234:237], v216 offset:49280
	s_addk_i32 s4, 0x400
	s_mov_b32 s5, m0
	s_mov_b32 m0, s4
	s_nop 0
	global_load_lds_dwordx4 v198, s[70:71]
	s_mov_b32 m0, s5
	v_exp_f32_e32 v25, v26
	v_exp_f32_e32 v26, v27
	v_exp_f32_e32 v27, v28
	s_waitcnt lgkmcnt(4)
	v_mfma_f32_32x32x16_bf16 v[112:127], v[238:241], v[176:179], v[112:127]
	ds_read_b128 v[238:241], v216 offset:57472
	v_exp_f32_e32 v28, v29
	v_exp_f32_e32 v29, v30
	v_exp_f32_e32 v30, v31
	v_exp_f32_e32 v31, v128
	s_waitcnt lgkmcnt(4)
	v_mfma_f32_32x32x16_bf16 v[96:111], v[242:245], v[176:179], v[96:111]
	ds_read_b128 v[242:245], v233 offset:49280
	v_exp_f32_e32 v128, v129
	v_exp_f32_e32 v129, v130
	v_exp_f32_e32 v130, v131
	v_exp_f32_e32 v131, v132
	s_waitcnt lgkmcnt(4)
	v_mfma_f32_32x32x16_bf16 v[112:127], v[246:249], v[172:175], v[112:127]
	ds_read_b128 v[246:249], v233 offset:57472
	s_add_u32 s4, s56, 0x4000
	s_addc_u32 s5, s57, 0
	s_add_i32 s72, s74, s97
	s_mov_b32 s73, m0
	s_mov_b32 m0, s72
	s_nop 0
	global_load_lds_dwordx4 v199, s[4:5]
	s_mov_b32 m0, s73
	v_exp_f32_e32 v132, v133
	v_exp_f32_e32 v133, v134
	v_exp_f32_e32 v134, v5
	s_waitcnt lgkmcnt(4)
	v_mfma_f32_32x32x16_bf16 v[96:111], v[250:253], v[172:175], v[96:111]
	ds_read_b128 v[250:253], v254 offset:49280
	v_add_f32_e32 v5, v136, v135
	v_add_f32_e32 v5, v137, v5
	v_add_f32_e32 v5, v138, v5
	v_add_f32_e32 v5, v10, v5
	v_add_f32_e32 v5, v11, v5
	v_add_f32_e32 v5, v12, v5
	v_add_f32_e32 v5, v13, v5
	s_waitcnt lgkmcnt(4)
	v_mfma_f32_32x32x16_bf16 v[112:127], v[234:237], v[168:171], v[112:127]
	ds_read_b128 v[234:237], v254 offset:57472
	v_add_f32_e32 v5, v14, v5
	v_add_f32_e32 v5, v15, v5
	v_add_f32_e32 v5, v18, v5
	v_add_f32_e32 v5, v19, v5
	v_add_f32_e32 v5, v20, v5
	v_add_f32_e32 v5, v21, v5
	v_add_f32_e32 v5, v22, v5
	s_waitcnt lgkmcnt(4)
	v_mfma_f32_32x32x16_bf16 v[96:111], v[238:241], v[168:171], v[96:111]
	s_addk_i32 s72, 0x400
	s_mov_b32 s73, m0
	s_mov_b32 m0, s72
	s_nop 0
	global_load_lds_dwordx4 v200, s[4:5]
	s_mov_b32 m0, s73
	v_add_f32_e32 v5, v23, v5
	v_add_f32_e32 v5, v7, v5
	v_add_f32_e32 v5, v24, v5
	v_add_f32_e32 v5, v25, v5
	v_add_f32_e32 v5, v26, v5
	v_add_f32_e32 v5, v27, v5
	v_add_f32_e32 v5, v28, v5
	s_waitcnt lgkmcnt(3)
	v_mfma_f32_32x32x16_bf16 v[112:127], v[242:245], v[164:167], v[112:127]
	v_add_f32_e32 v5, v29, v5
	v_add_f32_e32 v5, v30, v5
	v_add_f32_e32 v5, v31, v5
	v_add_f32_e32 v5, v128, v5
	v_add_f32_e32 v5, v129, v5
	v_add_f32_e32 v5, v130, v5
	v_add_f32_e32 v5, v131, v5
	s_waitcnt lgkmcnt(2)
	v_mfma_f32_32x32x16_bf16 v[96:111], v[246:249], v[164:167], v[96:111]
	v_add_f32_e32 v5, v132, v5
	v_add_f32_e32 v5, v133, v5
	v_add_f32_e32 v5, v134, v5
	v_mov_b32_e32 v6, v5
	v_cvt_pk_bf16_f32 v8, v135, v136
	v_cvt_pk_bf16_f32 v9, v137, v138
	v_cvt_pk_bf16_f32 v10, v10, v11
	s_waitcnt lgkmcnt(1)
	v_mfma_f32_32x32x16_bf16 v[112:127], v[250:253], v[160:163], v[112:127]
	s_nop 1
	v_permlane32_swap_b32_e32 v5, v6
	v_cvt_pk_bf16_f32 v11, v12, v13
	v_cvt_pk_bf16_f32 v12, v14, v15
	v_cvt_pk_bf16_f32 v13, v18, v19
	v_cvt_pk_bf16_f32 v14, v20, v21
	v_cvt_pk_bf16_f32 v15, v22, v23
	v_cvt_pk_bf16_f32 v18, v7, v24
	s_waitcnt lgkmcnt(0)
	v_mfma_f32_32x32x16_bf16 v[96:111], v[234:237], v[160:163], v[96:111]
	v_cvt_pk_bf16_f32 v19, v25, v26
	v_cvt_pk_bf16_f32 v20, v27, v28
	v_cvt_pk_bf16_f32 v21, v29, v30
	v_cvt_pk_bf16_f32 v22, v31, v128
	v_cvt_pk_bf16_f32 v23, v129, v130
	v_cvt_pk_bf16_f32 v24, v131, v132
	v_cvt_pk_bf16_f32 v25, v133, v134
	s_setprio 0
	v_add_u32_e32 v7, s77, v206
	ds_read_b64_tr_b16 v[26:27], v7 offset:0
	ds_read_b64_tr_b16 v[28:29], v7 offset:0x800
	ds_read_b64_tr_b16 v[128:129], v7 offset:0x1000
	ds_read_b64_tr_b16 v[130:131], v7 offset:0x1800
	ds_read_b64_tr_b16 v[132:133], v7 offset:0x2000
	ds_read_b64_tr_b16 v[134:135], v7 offset:0x2800
	ds_read_b64_tr_b16 v[136:137], v7 offset:0x3000
	ds_read_b64_tr_b16 v[138:139], v7 offset:0x3800
	s_waitcnt lgkmcnt(6)
	s_nop 0
	v_mfma_f32_32x32x16_bf16 v[32:47], v[8:11], v[26:29], v[32:47]
	ds_read_b64_tr_b16 v[26:27], v7 offset:0x200
	ds_read_b64_tr_b16 v[28:29], v7 offset:0xa00
	s_waitcnt lgkmcnt(6)
	v_mfma_f32_32x32x16_bf16 v[32:47], v[12:15], v[128:131], v[32:47]
	ds_read_b64_tr_b16 v[128:129], v7 offset:0x1200
	ds_read_b64_tr_b16 v[130:131], v7 offset:0x1a00
	v_mul_f32_e32 v140, 0xbe0293ee, v2
	v_fmamk_f32 v230, v112, 0x3e0293ee, v140
	v_fmamk_f32 v232, v113, 0x3e0293ee, v140
	s_waitcnt lgkmcnt(6)
	v_mfma_f32_32x32x16_bf16 v[32:47], v[18:21], v[132:135], v[32:47]
	ds_read_b64_tr_b16 v[132:133], v7 offset:0x2200
	ds_read_b64_tr_b16 v[134:135], v7 offset:0x2a00
	v_exp_f32_e32 v230, v230
	v_exp_f32_e32 v232, v232
	v_fmamk_f32 v228, v114, 0x3e0293ee, v140
	v_fmamk_f32 v231, v115, 0x3e0293ee, v140
	s_waitcnt lgkmcnt(6)
	v_mfma_f32_32x32x16_bf16 v[32:47], v[22:25], v[136:139], v[32:47]
	ds_read_b64_tr_b16 v[136:137], v7 offset:0x3200
	ds_read_b64_tr_b16 v[138:139], v7 offset:0x3a00
	v_exp_f32_e32 v228, v228
	v_exp_f32_e32 v231, v231
	v_fmamk_f32 v226, v116, 0x3e0293ee, v140
	v_fmamk_f32 v229, v117, 0x3e0293ee, v140
	s_waitcnt lgkmcnt(6)
	v_mfma_f32_32x32x16_bf16 v[48:63], v[8:11], v[26:29], v[48:63]
	ds_read_b64_tr_b16 v[26:27], v7 offset:0x400
	ds_read_b64_tr_b16 v[28:29], v7 offset:0xc00
	v_exp_f32_e32 v226, v226
	v_exp_f32_e32 v229, v229
	v_fmamk_f32 v225, v118, 0x3e0293ee, v140
	v_fmamk_f32 v227, v119, 0x3e0293ee, v140
	s_waitcnt lgkmcnt(6)
	v_mfma_f32_32x32x16_bf16 v[48:63], v[12:15], v[128:131], v[48:63]
	ds_read_b64_tr_b16 v[128:129], v7 offset:0x1400
	ds_read_b64_tr_b16 v[130:131], v7 offset:0x1c00
	v_exp_f32_e32 v225, v225
	v_exp_f32_e32 v227, v227
	v_fmamk_f32 v222, v120, 0x3e0293ee, v140
	v_fmamk_f32 v224, v121, 0x3e0293ee, v140
	s_waitcnt lgkmcnt(6)
	v_mfma_f32_32x32x16_bf16 v[48:63], v[18:21], v[132:135], v[48:63]
	ds_read_b64_tr_b16 v[132:133], v7 offset:0x2400
	ds_read_b64_tr_b16 v[134:135], v7 offset:0x2c00
	v_exp_f32_e32 v222, v222
	v_exp_f32_e32 v224, v224
	v_fmamk_f32 v220, v122, 0x3e0293ee, v140
	v_fmamk_f32 v223, v123, 0x3e0293ee, v140
	s_waitcnt lgkmcnt(6)
	v_mfma_f32_32x32x16_bf16 v[48:63], v[22:25], v[136:139], v[48:63]
	ds_read_b64_tr_b16 v[136:137], v7 offset:0x3400
	ds_read_b64_tr_b16 v[138:139], v7 offset:0x3c00
	v_exp_f32_e32 v220, v220
	v_exp_f32_e32 v223, v223
	v_fmamk_f32 v218, v124, 0x3e0293ee, v140
	v_fmamk_f32 v221, v125, 0x3e0293ee, v140
	s_waitcnt lgkmcnt(6)
	v_mfma_f32_32x32x16_bf16 v[64:79], v[8:11], v[26:29], v[64:79]
	ds_read_b64_tr_b16 v[26:27], v7 offset:0x600
	ds_read_b64_tr_b16 v[28:29], v7 offset:0xe00
	v_exp_f32_e32 v218, v218
	v_exp_f32_e32 v221, v221
	v_fmamk_f32 v217, v126, 0x3e0293ee, v140
	v_fmamk_f32 v219, v127, 0x3e0293ee, v140
	s_waitcnt lgkmcnt(6)
	v_mfma_f32_32x32x16_bf16 v[64:79], v[12:15], v[128:131], v[64:79]
	ds_read_b64_tr_b16 v[128:129], v7 offset:0x1600
	ds_read_b64_tr_b16 v[130:131], v7 offset:0x1e00
	v_exp_f32_e32 v217, v217
	v_exp_f32_e32 v219, v219
	s_waitcnt lgkmcnt(6)
	v_mfma_f32_32x32x16_bf16 v[64:79], v[18:21], v[132:135], v[64:79]
	ds_read_b64_tr_b16 v[132:133], v7 offset:0x2600
	ds_read_b64_tr_b16 v[134:135], v7 offset:0x2e00
	v_add3_u32 v215, s74, v209, v208
	v_add3_u32 v216, s74, v210, v208
	s_waitcnt lgkmcnt(6)
	v_mfma_f32_32x32x16_bf16 v[64:79], v[22:25], v[136:139], v[64:79]
	ds_read_b64_tr_b16 v[136:137], v7 offset:0x3600
	ds_read_b64_tr_b16 v[138:139], v7 offset:0x3e00
	v_add3_u32 v233, s74, v211, v208
	v_add3_u32 v254, s74, v212, v208
	s_waitcnt lgkmcnt(6)
	v_mfma_f32_32x32x16_bf16 v[80:95], v[8:11], v[26:29], v[80:95]
	v_max_f32_e32 v7, v113, v112
	v_max3_f32 v7, v7, v114, v115
	v_max3_f32 v7, v7, v116, v117
	v_max3_f32 v7, v7, v118, v119
	v_max3_f32 v7, v7, v120, v121
	v_max3_f32 v7, v7, v122, v123
	v_max3_f32 v7, v7, v124, v125
	v_max3_f32 v7, v7, v126, v127
	s_waitcnt lgkmcnt(4)
	v_mfma_f32_32x32x16_bf16 v[80:95], v[12:15], v[128:131], v[80:95]
	v_max3_f32 v7, v7, v96, v97
	v_max3_f32 v7, v7, v98, v99
	v_max3_f32 v7, v7, v100, v101
	v_max3_f32 v7, v7, v102, v103
	v_max3_f32 v7, v7, v104, v105
	v_max3_f32 v7, v7, v106, v107
	v_max3_f32 v7, v7, v108, v109
	v_max3_f32 v7, v7, v110, v111
	s_waitcnt lgkmcnt(2)
	v_mfma_f32_32x32x16_bf16 v[80:95], v[18:21], v[132:135], v[80:95]
	v_sub_f32_e32 v8, v7, v2
	v_cmp_ge_f32_e32 vcc, 0x42b504f3, v8
	s_waitcnt lgkmcnt(0)
	v_mfma_f32_32x32x16_bf16 v[80:95], v[22:25], v[136:139], v[80:95]
	s_cmp_eq_u64 vcc, exec
	s_cbranch_scc0 .Lattn0_slowB
	v_mov_b32_e32 v7, 1.0
	v_mov_b32_e32 v214, v2

.Lattn0_slowA:
	v_mov_b32_e32 v4, v2
	s_nop 1
	v_permlane32_swap_b32_e32 v2, v4
	v_max_f32_e32 v2, v4, v2
	v_max_f32_e32 v2, v214, v2
	v_sub_f32_e32 v4, v214, v2
	v_mul_f32_e32 v4, 0x3e0293ee, v4
	v_exp_f32_e32 v4, v4
	s_nop 0
	v_cmp_gt_f32_e32 vcc, 1.0, v4
	s_cbranch_vccz .Lattn0_backA
	s_and_saveexec_b64 s[72:73], s[2:3]
	ds_write_b32 v204, v4 offset:128
	s_or_b64 exec, exec, s[72:73]
	s_waitcnt lgkmcnt(0)
	ds_read_b128 v[6:9], v203 offset:224
	ds_read_b128 v[10:13], v203 offset:192
	ds_read_b128 v[18:21], v203 offset:160
	ds_read_b128 v[22:25], v203 offset:128
	s_waitcnt lgkmcnt(3)
	v_pk_mul_f32 v[46:47], v[46:47], v[8:9]
	s_waitcnt lgkmcnt(2)
	v_pk_mul_f32 v[42:43], v[42:43], v[12:13]
	s_waitcnt lgkmcnt(1)
	v_pk_mul_f32 v[38:39], v[38:39], v[20:21]
	s_waitcnt lgkmcnt(0)
	v_pk_mul_f32 v[34:35], v[34:35], v[24:25]
	v_pk_mul_f32 v[44:45], v[44:45], v[6:7]
	v_pk_mul_f32 v[40:41], v[40:41], v[10:11]
	v_pk_mul_f32 v[36:37], v[36:37], v[18:19]
	v_pk_mul_f32 v[32:33], v[32:33], v[22:23]
	v_pk_mul_f32 v[62:63], v[62:63], v[8:9]
	v_pk_mul_f32 v[58:59], v[58:59], v[12:13]
	v_pk_mul_f32 v[54:55], v[54:55], v[20:21]
	v_pk_mul_f32 v[50:51], v[50:51], v[24:25]
	v_pk_mul_f32 v[60:61], v[60:61], v[6:7]
	v_pk_mul_f32 v[56:57], v[56:57], v[10:11]
	v_pk_mul_f32 v[52:53], v[52:53], v[18:19]
	v_pk_mul_f32 v[48:49], v[48:49], v[22:23]
	v_pk_mul_f32 v[78:79], v[78:79], v[8:9]
	v_pk_mul_f32 v[74:75], v[74:75], v[12:13]
	v_pk_mul_f32 v[70:71], v[70:71], v[20:21]
	v_pk_mul_f32 v[66:67], v[66:67], v[24:25]
	v_pk_mul_f32 v[76:77], v[76:77], v[6:7]
	v_pk_mul_f32 v[72:73], v[72:73], v[10:11]
	v_pk_mul_f32 v[68:69], v[68:69], v[18:19]
	v_pk_mul_f32 v[64:65], v[64:65], v[22:23]
	v_pk_mul_f32 v[94:95], v[94:95], v[8:9]
	v_pk_mul_f32 v[90:91], v[90:91], v[12:13]
	v_pk_mul_f32 v[86:87], v[86:87], v[20:21]
	v_pk_mul_f32 v[82:83], v[82:83], v[24:25]
	v_pk_mul_f32 v[92:93], v[92:93], v[6:7]
	v_pk_mul_f32 v[88:89], v[88:89], v[10:11]
	v_pk_mul_f32 v[84:85], v[84:85], v[18:19]
	v_pk_mul_f32 v[80:81], v[80:81], v[22:23]
	s_branch .Lattn0_backA
.Lattn0_slowB:
	v_mov_b32_e32 v8, v7
	s_nop 1
	v_permlane32_swap_b32_e32 v7, v8
	v_max_f32_e32 v7, v8, v7
	v_max_f32_e32 v8, v2, v7
	v_sub_f32_e32 v7, v2, v8
	v_mul_f32_e32 v7, 0x3e0293ee, v7
	v_exp_f32_e32 v7, v7
	v_mov_b32_e32 v214, v8
	v_cmp_gt_f32_e32 vcc, 1.0, v7
	s_cbranch_vccz .Lattn0_recompB
	s_and_saveexec_b64 s[72:73], s[2:3]
	ds_write_b32 v204, v7 offset:128
	s_or_b64 exec, exec, s[72:73]
	s_waitcnt lgkmcnt(0)
	ds_read_b128 v[10:13], v203 offset:224
	ds_read_b128 v[18:21], v203 offset:192
	ds_read_b128 v[22:25], v203 offset:160
	ds_read_b128 v[26:29], v203 offset:128
	s_waitcnt lgkmcnt(3)
	v_pk_mul_f32 v[46:47], v[46:47], v[12:13]
	s_waitcnt lgkmcnt(2)
	v_pk_mul_f32 v[42:43], v[42:43], v[20:21]
	s_waitcnt lgkmcnt(1)
	v_pk_mul_f32 v[38:39], v[38:39], v[24:25]
	s_waitcnt lgkmcnt(0)
	v_pk_mul_f32 v[34:35], v[34:35], v[28:29]
	v_pk_mul_f32 v[44:45], v[44:45], v[10:11]
	v_pk_mul_f32 v[40:41], v[40:41], v[18:19]
	v_pk_mul_f32 v[36:37], v[36:37], v[22:23]
	v_pk_mul_f32 v[32:33], v[32:33], v[26:27]
	v_pk_mul_f32 v[62:63], v[62:63], v[12:13]
	v_pk_mul_f32 v[58:59], v[58:59], v[20:21]
	v_pk_mul_f32 v[54:55], v[54:55], v[24:25]
	v_pk_mul_f32 v[50:51], v[50:51], v[28:29]
	v_pk_mul_f32 v[60:61], v[60:61], v[10:11]
	v_pk_mul_f32 v[56:57], v[56:57], v[18:19]
	v_pk_mul_f32 v[52:53], v[52:53], v[22:23]
	v_pk_mul_f32 v[48:49], v[48:49], v[26:27]
	v_pk_mul_f32 v[78:79], v[78:79], v[12:13]
	v_pk_mul_f32 v[74:75], v[74:75], v[20:21]
	v_pk_mul_f32 v[70:71], v[70:71], v[24:25]
	v_pk_mul_f32 v[66:67], v[66:67], v[28:29]
	v_pk_mul_f32 v[76:77], v[76:77], v[10:11]
	v_pk_mul_f32 v[72:73], v[72:73], v[18:19]
	v_pk_mul_f32 v[68:69], v[68:69], v[22:23]
	v_pk_mul_f32 v[64:65], v[64:65], v[26:27]
	v_pk_mul_f32 v[94:95], v[94:95], v[12:13]
	v_pk_mul_f32 v[90:91], v[90:91], v[20:21]
	v_pk_mul_f32 v[86:87], v[86:87], v[24:25]
	v_pk_mul_f32 v[82:83], v[82:83], v[28:29]
	v_pk_mul_f32 v[92:93], v[92:93], v[10:11]
	v_pk_mul_f32 v[88:89], v[88:89], v[18:19]
	v_pk_mul_f32 v[84:85], v[84:85], v[22:23]
	v_pk_mul_f32 v[80:81], v[80:81], v[26:27]
